# v36: v30 + OUT(1) epilogue first pass: residual-row loads of batches 2-4 requested one/two batches ahead into unused VGPRs (4 serial round trips -> 1)
# baseline (speedup 1.0000x reference)
.LBB0_1709:
	v_readlane_b32 s36, v255, 31
	s_lshl_b32 s18, s36, 8
	v_mov_b32_e32 v195, v184
	v_mov_b32_e32 v202, v185
	s_or_b32 s18, s18, s67
	v_readlane_b32 s37, v255, 32
	v_lshl_add_u32 v160, v202, 3, s18
	s_ashr_i32 s18, s84, 31
	s_lshr_b32 s18, s18, 29
	s_add_i32 s18, s84, s18
	s_ashr_i32 s18, s18, 3
	s_mul_i32 s36, s18, 3
	s_ashr_i32 s37, s36, 31
	s_lshl_b64 s[36:37], s[36:37], 12
	s_add_u32 s36, s60, s36
	s_addc_u32 s37, s61, s37
	s_lshl_b32 s18, s84, 8
	v_add_u32_e32 v193, s66, v195
	v_add_u32_e32 v178, s18, v193
	v_ashrrev_i32_e32 v179, 31, v178
	v_ashrrev_i32_e32 v161, 31, v160
	v_lshlrev_b64 v[162:163], 12, v[178:179]
	v_lshlrev_b64 v[180:181], 1, v[160:161]
	v_lshl_add_u64 v[128:129], s[74:75], 0, v[162:163]
	v_lshl_add_u64 v[130:131], v[128:129], 0, v[180:181]
	v_lshl_add_u64 v[182:183], v[180:181], 0, s[22:23]
	global_load_dwordx4 v[166:169], v[130:131], off
	v_lshl_add_u64 v[128:129], v[128:129], 0, v[182:183]
	global_load_dwordx4 v[170:173], v[128:129], off
	v_lshl_add_u64 v[132:133], v[160:161], 2, s[36:37]
	global_load_dwordx4 v[136:139], v[132:133], off
	global_load_dwordx4 v[128:131], v[132:133], off offset:16
	global_load_dwordx4 v[140:143], v[132:133], off offset:512
	s_nop 0
	global_load_dwordx4 v[132:135], v[132:133], off offset:528
	v_add_u32_e32 v144, 16, v178
	v_ashrrev_i32_e32 v145, 31, v144
	v_lshlrev_b64 v[164:165], 12, v[144:145]
	v_lshl_add_u64 v[144:145], s[74:75], 0, v[164:165]
	v_lshl_add_u64 v[146:147], v[144:145], 0, v[180:181]
	v_lshl_add_u64 v[144:145], v[144:145], 0, v[182:183]
	global_load_dwordx4 v[148:151], v[146:147], off
	s_nop 0
	global_load_dwordx4 v[144:147], v[144:145], off
	v_add_u32_e32 v244, 32, v178
	v_ashrrev_i32_e32 v245, 31, v244
	v_lshlrev_b64 v[244:245], 12, v[244:245]
	v_lshl_add_u64 v[244:245], s[74:75], 0, v[244:245]
	v_lshl_add_u64 v[212:213], v[244:245], 0, v[180:181]
	global_load_dwordx4 v[212:215], v[212:213], off
	v_lshl_add_u64 v[216:217], v[244:245], 0, v[182:183]
	global_load_dwordx4 v[216:219], v[216:217], off
	v_add_u32_e32 v244, 48, v178
	v_ashrrev_i32_e32 v245, 31, v244
	v_lshlrev_b64 v[244:245], 12, v[244:245]
	v_lshl_add_u64 v[244:245], s[74:75], 0, v[244:245]
	v_lshl_add_u64 v[220:221], v[244:245], 0, v[180:181]
	global_load_dwordx4 v[220:223], v[220:221], off
	v_lshl_add_u64 v[224:225], v[244:245], 0, v[182:183]
	global_load_dwordx4 v[224:227], v[224:225], off
	v_add_u32_e32 v244, 0x80, v178
	v_ashrrev_i32_e32 v245, 31, v244
	v_lshlrev_b64 v[244:245], 12, v[244:245]
	v_lshl_add_u64 v[244:245], s[74:75], 0, v[244:245]
	v_lshl_add_u64 v[228:229], v[244:245], 0, v[180:181]
	global_load_dwordx4 v[228:231], v[228:229], off
	v_lshl_add_u64 v[232:233], v[244:245], 0, v[182:183]
	global_load_dwordx4 v[232:235], v[232:233], off
	v_add_u32_e32 v244, 0x90, v178
	v_ashrrev_i32_e32 v245, 31, v244
	v_lshlrev_b64 v[244:245], 12, v[244:245]
	v_lshl_add_u64 v[244:245], s[74:75], 0, v[244:245]
	v_lshl_add_u64 v[236:237], v[244:245], 0, v[180:181]
	global_load_dwordx4 v[236:239], v[236:237], off
	v_lshl_add_u64 v[240:241], v[244:245], 0, v[182:183]
	global_load_dwordx4 v[240:243], v[240:241], off
	v_and_b32_e32 v175, 64, v191
	v_xor_b32_e32 v174, 16, v191
	v_add_u32_e32 v179, 64, v175
	v_cmp_lt_i32_e32 vcc, v174, v179
	v_lshl_add_u32 v195, v195, 2, s70
	s_waitcnt vmcnt(8)
	v_and_b32_e32 v175, 0xffff0000, v166
	v_cndmask_b32_e32 v174, v191, v174, vcc
	v_lshlrev_b32_e32 v194, 2, v174
	v_lshlrev_b32_e32 v174, 16, v166
	v_lshlrev_b32_e32 v176, 16, v167
	v_and_b32_e32 v177, 0xffff0000, v167
	v_lshlrev_b32_e32 v196, 16, v168
	v_and_b32_e32 v197, 0xffff0000, v168
	v_lshlrev_b32_e32 v168, 16, v169
	v_and_b32_e32 v169, 0xffff0000, v169
	v_lshlrev_b32_e32 v198, 16, v170
	v_and_b32_e32 v199, 0xffff0000, v170
	v_lshlrev_b32_e32 v170, 16, v171
	v_and_b32_e32 v171, 0xffff0000, v171
	v_lshlrev_b32_e32 v200, 16, v172
	v_and_b32_e32 v201, 0xffff0000, v172
	v_lshlrev_b32_e32 v172, 16, v173
	v_and_b32_e32 v173, 0xffff0000, v173
	v_pk_fma_f32 v[166:167], v[124:125], v[136:137], v[174:175]
	v_pk_fma_f32 v[126:127], v[126:127], v[138:139], v[176:177]
	v_pk_fma_f32 v[124:125], v[120:121], v[128:129], v[196:197]
	v_pk_fma_f32 v[122:123], v[122:123], v[130:131], v[168:169]
	v_pk_fma_f32 v[120:121], v[116:117], v[140:141], v[198:199]
	v_pk_fma_f32 v[116:117], v[118:119], v[142:143], v[170:171]
	v_pk_fma_f32 v[114:115], v[114:115], v[134:135], v[172:173]
	v_pk_mul_f32 v[118:119], v[166:167], v[166:167]
	v_pk_mul_f32 v[168:169], v[126:127], v[126:127]
	v_pk_mul_f32 v[170:171], v[124:125], v[124:125]
	v_pk_mul_f32 v[172:173], v[122:123], v[122:123]
	v_pk_fma_f32 v[112:113], v[112:113], v[132:133], v[200:201]
	v_pk_mul_f32 v[174:175], v[120:121], v[120:121]
	v_pk_mul_f32 v[176:177], v[116:117], v[116:117]
	v_add_f32_e32 v172, v172, v173
	v_add_f32_e32 v170, v170, v171
	v_add_f32_e32 v168, v168, v169
	v_add_f32_e32 v118, v118, v119
	v_pk_mul_f32 v[196:197], v[112:113], v[112:113]
	v_pk_mul_f32 v[198:199], v[114:115], v[114:115]
	v_add_f32_e32 v119, v176, v177
	v_add_f32_e32 v169, v174, v175
	v_add_f32_e32 v170, v170, v172
	v_add_f32_e32 v118, v118, v168
	v_add_f32_e32 v171, v198, v199
	v_add_f32_e32 v173, v196, v197
	v_add_f32_e32 v119, v169, v119
	v_add_f32_e32 v118, v118, v170
	v_add_f32_e32 v118, v118, v119
	v_add_f32_e32 v119, v173, v171
	v_add_f32_e32 v118, v119, v118
	ds_bpermute_b32 v119, v194, v118
	v_xor_b32_e32 v168, 32, v191
	v_cmp_lt_i32_e32 vcc, v168, v179
	s_waitcnt lgkmcnt(0)
	v_add_f32_e32 v118, v118, v119
	v_cndmask_b32_e32 v168, v191, v168, vcc
	v_lshlrev_b32_e32 v196, 2, v168
	ds_bpermute_b32 v119, v196, v118
	v_cmp_eq_u32_e32 vcc, 0, v202
	s_and_saveexec_b64 s[36:37], vcc
	s_cbranch_execz .LBB0_1711
	s_waitcnt lgkmcnt(0)
	v_add_f32_e32 v118, v118, v119
	ds_write_b32 v195, v118

.LBB0_1713:
	s_or_b64 exec, exec, s[36:37]
	v_add_u32_e32 v96, 32, v178
	s_waitcnt lgkmcnt(0)
	v_ashrrev_i32_e32 v97, 31, v96
	v_lshlrev_b64 v[168:169], 12, v[96:97]
	v_lshl_add_u64 v[96:97], s[74:75], 0, v[168:169]
	v_lshl_add_u64 v[98:99], v[96:97], 0, v[180:181]
	s_waitcnt vmcnt(4)
	v_mov_b64_e32 v[170:171], v[212:213]
	v_mov_b64_e32 v[172:173], v[214:215]
	v_lshl_add_u64 v[96:97], v[96:97], 0, v[182:183]
	v_mov_b64_e32 v[174:175], v[216:217]
	v_mov_b64_e32 v[176:177], v[218:219]
	v_add_u32_e32 v96, 48, v178
	v_ashrrev_i32_e32 v97, 31, v96
	v_lshlrev_b64 v[144:145], 12, v[96:97]
	v_lshl_add_u64 v[96:97], s[74:75], 0, v[144:145]
	v_lshl_add_u64 v[98:99], v[96:97], 0, v[180:181]
	v_lshl_add_u64 v[96:97], v[96:97], 0, v[182:183]
	v_mov_b64_e32 v[100:101], v[220:221]
	v_mov_b64_e32 v[102:103], v[222:223]
	s_nop 0
	v_mov_b64_e32 v[96:97], v[224:225]
	v_mov_b64_e32 v[98:99], v[226:227]
	v_add_u32_e32 v244, 0xa0, v178
	v_ashrrev_i32_e32 v245, 31, v244
	v_lshlrev_b64 v[244:245], 12, v[244:245]
	v_lshl_add_u64 v[244:245], s[74:75], 0, v[244:245]
	v_lshl_add_u64 v[212:213], v[244:245], 0, v[180:181]
	global_load_dwordx4 v[212:215], v[212:213], off
	v_lshl_add_u64 v[216:217], v[244:245], 0, v[182:183]
	global_load_dwordx4 v[216:219], v[216:217], off
	v_add_u32_e32 v244, 0xb0, v178
	v_ashrrev_i32_e32 v245, 31, v244
	v_lshlrev_b64 v[244:245], 12, v[244:245]
	v_lshl_add_u64 v[244:245], s[74:75], 0, v[244:245]
	v_lshl_add_u64 v[220:221], v[244:245], 0, v[180:181]
	global_load_dwordx4 v[220:223], v[220:221], off
	v_lshl_add_u64 v[224:225], v[244:245], 0, v[182:183]
	global_load_dwordx4 v[224:227], v[224:225], off
	s_nop 0
	v_lshlrev_b32_e32 v198, 16, v170
	v_and_b32_e32 v199, 0xffff0000, v170
	v_lshlrev_b32_e32 v200, 16, v171
	v_and_b32_e32 v201, 0xffff0000, v171
	v_lshlrev_b32_e32 v202, 16, v172
	v_and_b32_e32 v203, 0xffff0000, v172
	v_lshlrev_b32_e32 v172, 16, v173
	v_and_b32_e32 v173, 0xffff0000, v173
	s_nop 0
	v_lshlrev_b32_e32 v204, 16, v174
	v_and_b32_e32 v205, 0xffff0000, v174
	v_lshlrev_b32_e32 v174, 16, v175
	v_and_b32_e32 v175, 0xffff0000, v175
	v_lshlrev_b32_e32 v206, 16, v176
	v_and_b32_e32 v207, 0xffff0000, v176
	v_lshlrev_b32_e32 v176, 16, v177
	v_and_b32_e32 v177, 0xffff0000, v177
	v_pk_fma_f32 v[170:171], v[92:93], v[136:137], v[198:199]
	v_pk_fma_f32 v[94:95], v[94:95], v[138:139], v[200:201]
	v_pk_fma_f32 v[92:93], v[88:89], v[128:129], v[202:203]
	v_pk_fma_f32 v[90:91], v[90:91], v[130:131], v[172:173]
	v_pk_fma_f32 v[88:89], v[84:85], v[140:141], v[204:205]
	v_pk_fma_f32 v[84:85], v[86:87], v[142:143], v[174:175]
	v_pk_fma_f32 v[82:83], v[82:83], v[134:135], v[176:177]
	v_pk_mul_f32 v[86:87], v[170:171], v[170:171]
	v_pk_mul_f32 v[172:173], v[94:95], v[94:95]
	v_pk_mul_f32 v[174:175], v[92:93], v[92:93]
	v_pk_mul_f32 v[176:177], v[90:91], v[90:91]
	v_pk_fma_f32 v[80:81], v[80:81], v[132:133], v[206:207]
	v_pk_mul_f32 v[198:199], v[88:89], v[88:89]
	v_pk_mul_f32 v[200:201], v[84:85], v[84:85]
	v_add_f32_e32 v176, v176, v177
	v_add_f32_e32 v174, v174, v175
	v_add_f32_e32 v172, v172, v173
	v_add_f32_e32 v86, v86, v87
	v_pk_mul_f32 v[202:203], v[80:81], v[80:81]
	v_pk_mul_f32 v[204:205], v[82:83], v[82:83]
	v_add_f32_e32 v87, v200, v201
	v_add_f32_e32 v173, v198, v199
	v_add_f32_e32 v174, v174, v176
	v_add_f32_e32 v86, v86, v172
	v_add_f32_e32 v175, v204, v205
	v_add_f32_e32 v177, v202, v203
	v_add_f32_e32 v87, v173, v87
	v_add_f32_e32 v86, v86, v174
	v_add_f32_e32 v86, v86, v87
	v_add_f32_e32 v87, v177, v175
	v_add_f32_e32 v86, v87, v86
	ds_bpermute_b32 v87, v194, v86
	s_waitcnt lgkmcnt(0)
	v_add_f32_e32 v86, v86, v87
	ds_bpermute_b32 v87, v196, v86
	s_and_saveexec_b64 s[36:37], vcc
	s_cbranch_execz .LBB0_1715
	s_waitcnt lgkmcnt(0)
	v_add_f32_e32 v86, v86, v87
	ds_write_b32 v195, v86 offset:128
.LBB0_1715:
	s_or_b64 exec, exec, s[36:37]
	s_nop 0
	v_lshlrev_b32_e32 v86, 16, v100
	s_waitcnt lgkmcnt(0)
	v_and_b32_e32 v87, 0xffff0000, v100
	v_pk_fma_f32 v[76:77], v[76:77], v[136:137], v[86:87]
	v_lshlrev_b32_e32 v86, 16, v101
	v_and_b32_e32 v87, 0xffff0000, v101
	v_pk_fma_f32 v[78:79], v[78:79], v[138:139], v[86:87]
	v_lshlrev_b32_e32 v86, 16, v102
	v_and_b32_e32 v87, 0xffff0000, v102
	v_pk_fma_f32 v[72:73], v[72:73], v[128:129], v[86:87]
	v_lshlrev_b32_e32 v86, 16, v103
	v_and_b32_e32 v87, 0xffff0000, v103
	v_pk_fma_f32 v[74:75], v[74:75], v[130:131], v[86:87]
	s_nop 0
	v_lshlrev_b32_e32 v86, 16, v96
	v_and_b32_e32 v87, 0xffff0000, v96
	v_pk_mul_f32 v[176:177], v[72:73], v[72:73]
	v_pk_mul_f32 v[198:199], v[74:75], v[74:75]
	v_pk_fma_f32 v[86:87], v[68:69], v[140:141], v[86:87]
	v_lshlrev_b32_e32 v68, 16, v97
	v_and_b32_e32 v69, 0xffff0000, v97
	v_lshlrev_b32_e32 v96, 16, v98
	v_and_b32_e32 v97, 0xffff0000, v98
	v_pk_mul_f32 v[172:173], v[76:77], v[76:77]
	v_pk_mul_f32 v[174:175], v[78:79], v[78:79]
	v_pk_fma_f32 v[100:101], v[70:71], v[142:143], v[68:69]
	v_pk_fma_f32 v[102:103], v[64:65], v[132:133], v[96:97]
	v_lshlrev_b32_e32 v64, 16, v99
	v_and_b32_e32 v65, 0xffff0000, v99
	v_add_f32_e32 v96, v198, v199
	v_add_f32_e32 v97, v176, v177
	v_pk_mul_f32 v[68:69], v[86:87], v[86:87]
	v_pk_mul_f32 v[70:71], v[100:101], v[100:101]
	v_pk_fma_f32 v[98:99], v[66:67], v[134:135], v[64:65]
	v_add_f32_e32 v96, v97, v96
	v_add_f32_e32 v97, v174, v175
	v_add_f32_e32 v172, v172, v173
	v_pk_mul_f32 v[64:65], v[102:103], v[102:103]
	v_pk_mul_f32 v[66:67], v[98:99], v[98:99]
	v_add_f32_e32 v97, v172, v97
	v_add_f32_e32 v70, v70, v71
	v_add_f32_e32 v68, v68, v69
	v_add_f32_e32 v96, v97, v96
	v_add_f32_e32 v68, v68, v70
	v_add_f32_e32 v66, v66, v67
	v_add_f32_e32 v64, v64, v65
	v_add_f32_e32 v68, v96, v68
	v_add_f32_e32 v64, v64, v66
	v_add_f32_e32 v64, v64, v68
	ds_bpermute_b32 v65, v194, v64
	s_waitcnt lgkmcnt(0)
	v_add_f32_e32 v64, v64, v65
	ds_bpermute_b32 v65, v196, v64
	s_and_saveexec_b64 s[36:37], vcc
	s_cbranch_execz .LBB0_1717
	s_waitcnt lgkmcnt(0)
	v_add_f32_e32 v64, v64, v65
	ds_write_b32 v195, v64 offset:192
.LBB0_1717:
	s_or_b64 exec, exec, s[36:37]
	v_add_u32_e32 v64, 0x80, v178
	s_waitcnt lgkmcnt(0)
	v_ashrrev_i32_e32 v65, 31, v64
	v_lshlrev_b64 v[172:173], 12, v[64:65]
	v_lshl_add_u64 v[64:65], s[74:75], 0, v[172:173]
	v_lshl_add_u64 v[66:67], v[64:65], 0, v[180:181]
	s_waitcnt vmcnt(4)
	v_mov_b64_e32 v[174:175], v[228:229]
	v_mov_b64_e32 v[176:177], v[230:231]
	v_lshl_add_u64 v[64:65], v[64:65], 0, v[182:183]
	v_mov_b64_e32 v[198:199], v[232:233]
	v_mov_b64_e32 v[200:201], v[234:235]
	v_add_u32_e32 v64, 0x90, v178
	v_ashrrev_i32_e32 v65, 31, v64
	v_lshlrev_b64 v[96:97], 12, v[64:65]
	v_lshl_add_u64 v[64:65], s[74:75], 0, v[96:97]
	v_lshl_add_u64 v[66:67], v[64:65], 0, v[180:181]
	v_lshl_add_u64 v[64:65], v[64:65], 0, v[182:183]
	v_mov_b64_e32 v[68:69], v[236:237]
	v_mov_b64_e32 v[70:71], v[238:239]
	s_nop 0
	v_mov_b64_e32 v[64:65], v[240:241]
	v_mov_b64_e32 v[66:67], v[242:243]
	s_nop 0
	v_lshlrev_b32_e32 v202, 16, v174
	v_and_b32_e32 v203, 0xffff0000, v174
	v_lshlrev_b32_e32 v204, 16, v175
	v_and_b32_e32 v205, 0xffff0000, v175
	v_lshlrev_b32_e32 v206, 16, v176
	v_and_b32_e32 v207, 0xffff0000, v176
	v_lshlrev_b32_e32 v176, 16, v177
	v_and_b32_e32 v177, 0xffff0000, v177
	s_nop 0
	v_lshlrev_b32_e32 v208, 16, v198
	v_and_b32_e32 v209, 0xffff0000, v198
	v_lshlrev_b32_e32 v198, 16, v199
	v_and_b32_e32 v199, 0xffff0000, v199
	v_lshlrev_b32_e32 v210, 16, v200
	v_and_b32_e32 v211, 0xffff0000, v200
	v_lshlrev_b32_e32 v200, 16, v201
	v_and_b32_e32 v201, 0xffff0000, v201
	v_pk_fma_f32 v[174:175], v[60:61], v[136:137], v[202:203]
	v_pk_fma_f32 v[62:63], v[62:63], v[138:139], v[204:205]
	v_pk_fma_f32 v[60:61], v[56:57], v[128:129], v[206:207]
	v_pk_fma_f32 v[58:59], v[58:59], v[130:131], v[176:177]
	v_pk_fma_f32 v[56:57], v[52:53], v[140:141], v[208:209]
	v_pk_fma_f32 v[52:53], v[54:55], v[142:143], v[198:199]
	v_pk_fma_f32 v[50:51], v[50:51], v[134:135], v[200:201]
	v_pk_mul_f32 v[54:55], v[174:175], v[174:175]
	v_pk_mul_f32 v[176:177], v[62:63], v[62:63]
	v_pk_mul_f32 v[198:199], v[60:61], v[60:61]
	v_pk_mul_f32 v[200:201], v[58:59], v[58:59]
	v_pk_fma_f32 v[48:49], v[48:49], v[132:133], v[210:211]
	v_pk_mul_f32 v[202:203], v[56:57], v[56:57]
	v_pk_mul_f32 v[204:205], v[52:53], v[52:53]
	v_add_f32_e32 v179, v200, v201
	v_add_f32_e32 v197, v198, v199
	v_add_f32_e32 v176, v176, v177
	v_add_f32_e32 v54, v54, v55
	v_pk_mul_f32 v[206:207], v[48:49], v[48:49]
	v_pk_mul_f32 v[208:209], v[50:51], v[50:51]
	v_add_f32_e32 v55, v204, v205
	v_add_f32_e32 v177, v202, v203
	v_add_f32_e32 v179, v197, v179
	v_add_f32_e32 v54, v54, v176
	v_add_f32_e32 v198, v208, v209
	v_add_f32_e32 v199, v206, v207
	v_add_f32_e32 v55, v177, v55
	v_add_f32_e32 v54, v54, v179
	v_add_f32_e32 v54, v54, v55
	v_add_f32_e32 v55, v199, v198
	v_add_f32_e32 v54, v55, v54
	ds_bpermute_b32 v55, v194, v54
	s_waitcnt lgkmcnt(0)
	v_add_f32_e32 v54, v54, v55
	ds_bpermute_b32 v55, v196, v54
	s_and_saveexec_b64 s[36:37], vcc
	s_cbranch_execz .LBB0_1719
	s_waitcnt lgkmcnt(0)
	v_add_f32_e32 v54, v54, v55
	ds_write_b32 v195, v54 offset:256
.LBB0_1719:
	s_or_b64 exec, exec, s[36:37]
	s_nop 0
	v_lshlrev_b32_e32 v54, 16, v68
	s_waitcnt lgkmcnt(0)
	v_and_b32_e32 v55, 0xffff0000, v68
	v_pk_fma_f32 v[44:45], v[44:45], v[136:137], v[54:55]
	v_lshlrev_b32_e32 v54, 16, v69
	v_and_b32_e32 v55, 0xffff0000, v69
	v_pk_fma_f32 v[46:47], v[46:47], v[138:139], v[54:55]
	v_lshlrev_b32_e32 v54, 16, v70
	v_and_b32_e32 v55, 0xffff0000, v70
	v_pk_fma_f32 v[40:41], v[40:41], v[128:129], v[54:55]
	v_lshlrev_b32_e32 v54, 16, v71
	v_and_b32_e32 v55, 0xffff0000, v71
	v_pk_fma_f32 v[42:43], v[42:43], v[130:131], v[54:55]
	s_nop 0
	v_lshlrev_b32_e32 v54, 16, v64
	v_and_b32_e32 v55, 0xffff0000, v64
	v_pk_mul_f32 v[200:201], v[40:41], v[40:41]
	v_pk_mul_f32 v[202:203], v[42:43], v[42:43]
	v_pk_fma_f32 v[54:55], v[36:37], v[140:141], v[54:55]
	v_lshlrev_b32_e32 v36, 16, v65
	v_and_b32_e32 v37, 0xffff0000, v65
	v_lshlrev_b32_e32 v64, 16, v66
	v_and_b32_e32 v65, 0xffff0000, v66
	v_pk_mul_f32 v[176:177], v[44:45], v[44:45]
	v_pk_mul_f32 v[198:199], v[46:47], v[46:47]
	v_pk_fma_f32 v[68:69], v[38:39], v[142:143], v[36:37]
	v_pk_fma_f32 v[70:71], v[32:33], v[132:133], v[64:65]
	v_lshlrev_b32_e32 v32, 16, v67
	v_and_b32_e32 v33, 0xffff0000, v67
	v_add_f32_e32 v64, v202, v203
	v_add_f32_e32 v65, v200, v201
	v_pk_mul_f32 v[36:37], v[54:55], v[54:55]
	v_pk_mul_f32 v[38:39], v[68:69], v[68:69]
	v_pk_fma_f32 v[66:67], v[34:35], v[134:135], v[32:33]
	v_add_f32_e32 v64, v65, v64
	v_add_f32_e32 v65, v198, v199
	v_add_f32_e32 v176, v176, v177
	v_pk_mul_f32 v[32:33], v[70:71], v[70:71]
	v_pk_mul_f32 v[34:35], v[66:67], v[66:67]
	v_add_f32_e32 v65, v176, v65
	v_add_f32_e32 v38, v38, v39
	v_add_f32_e32 v36, v36, v37
	v_add_f32_e32 v64, v65, v64
	v_add_f32_e32 v36, v36, v38
	v_add_f32_e32 v34, v34, v35
	v_add_f32_e32 v32, v32, v33
	v_add_f32_e32 v36, v64, v36
	v_add_f32_e32 v32, v32, v34
	v_add_f32_e32 v32, v32, v36
	ds_bpermute_b32 v33, v194, v32
	s_waitcnt lgkmcnt(0)
	v_add_f32_e32 v32, v32, v33
	ds_bpermute_b32 v33, v196, v32
	s_and_saveexec_b64 s[36:37], vcc
	s_cbranch_execz .LBB0_1721
	s_waitcnt lgkmcnt(0)
	v_add_f32_e32 v32, v32, v33
	ds_write_b32 v195, v32 offset:320
.LBB0_1721:
	s_or_b64 exec, exec, s[36:37]
	v_add_u32_e32 v32, 0xa0, v178
	s_waitcnt lgkmcnt(0)
	v_ashrrev_i32_e32 v33, 31, v32
	v_lshlrev_b64 v[176:177], 12, v[32:33]
	v_lshl_add_u64 v[32:33], s[74:75], 0, v[176:177]
	v_lshl_add_u64 v[34:35], v[32:33], 0, v[180:181]
	s_waitcnt vmcnt(0)
	v_mov_b64_e32 v[198:199], v[212:213]
	v_mov_b64_e32 v[200:201], v[214:215]
	v_lshl_add_u64 v[32:33], v[32:33], 0, v[182:183]
	v_mov_b64_e32 v[202:203], v[216:217]
	v_mov_b64_e32 v[204:205], v[218:219]
	v_add_u32_e32 v32, 0xb0, v178
	v_ashrrev_i32_e32 v33, 31, v32
	v_lshlrev_b64 v[64:65], 12, v[32:33]
	v_lshl_add_u64 v[32:33], s[74:75], 0, v[64:65]
	v_lshl_add_u64 v[34:35], v[32:33], 0, v[180:181]
	v_lshl_add_u64 v[32:33], v[32:33], 0, v[182:183]
	v_mov_b64_e32 v[36:37], v[220:221]
	v_mov_b64_e32 v[38:39], v[222:223]
	s_nop 0
	v_mov_b64_e32 v[32:33], v[224:225]
	v_mov_b64_e32 v[34:35], v[226:227]
	s_nop 0
	v_lshlrev_b32_e32 v178, 16, v198
	v_and_b32_e32 v179, 0xffff0000, v198
	v_lshlrev_b32_e32 v180, 16, v199
	v_and_b32_e32 v181, 0xffff0000, v199
	v_lshlrev_b32_e32 v182, 16, v200
	v_and_b32_e32 v183, 0xffff0000, v200
	v_lshlrev_b32_e32 v198, 16, v201
	v_and_b32_e32 v199, 0xffff0000, v201
	s_nop 0
	v_lshlrev_b32_e32 v200, 16, v202
	v_and_b32_e32 v201, 0xffff0000, v202
	v_lshlrev_b32_e32 v202, 16, v203
	v_and_b32_e32 v203, 0xffff0000, v203
	v_pk_fma_f32 v[178:179], v[28:29], v[136:137], v[178:179]
	v_pk_fma_f32 v[30:31], v[30:31], v[138:139], v[180:181]
	v_pk_fma_f32 v[28:29], v[24:25], v[128:129], v[182:183]
	v_pk_fma_f32 v[26:27], v[26:27], v[130:131], v[198:199]
	v_lshlrev_b32_e32 v206, 16, v204
	v_and_b32_e32 v207, 0xffff0000, v204
	v_lshlrev_b32_e32 v204, 16, v205
	v_and_b32_e32 v205, 0xffff0000, v205
	v_pk_fma_f32 v[24:25], v[20:21], v[140:141], v[200:201]
	v_pk_fma_f32 v[20:21], v[22:23], v[142:143], v[202:203]
	v_pk_mul_f32 v[22:23], v[178:179], v[178:179]
	v_pk_mul_f32 v[180:181], v[30:31], v[30:31]
	v_pk_mul_f32 v[182:183], v[28:29], v[28:29]
	v_pk_mul_f32 v[198:199], v[26:27], v[26:27]
	v_pk_fma_f32 v[16:17], v[16:17], v[132:133], v[206:207]
	v_pk_fma_f32 v[18:19], v[18:19], v[134:135], v[204:205]
	v_pk_mul_f32 v[200:201], v[24:25], v[24:25]
	v_pk_mul_f32 v[202:203], v[20:21], v[20:21]
	v_add_f32_e32 v197, v198, v199
	v_add_f32_e32 v182, v182, v183
	v_add_f32_e32 v180, v180, v181
	v_add_f32_e32 v22, v22, v23
	v_pk_mul_f32 v[204:205], v[16:17], v[16:17]
	v_pk_mul_f32 v[206:207], v[18:19], v[18:19]
	v_add_f32_e32 v23, v202, v203
	v_add_f32_e32 v181, v200, v201
	v_add_f32_e32 v182, v182, v197
	v_add_f32_e32 v22, v22, v180
	v_add_f32_e32 v183, v206, v207
	v_add_f32_e32 v198, v204, v205
	v_add_f32_e32 v23, v181, v23
	v_add_f32_e32 v22, v22, v182
	v_add_f32_e32 v22, v22, v23
	v_add_f32_e32 v23, v198, v183
	v_add_f32_e32 v22, v23, v22
	ds_bpermute_b32 v23, v194, v22
	s_waitcnt lgkmcnt(0)
	v_add_f32_e32 v22, v22, v23
	ds_bpermute_b32 v23, v196, v22
	s_and_saveexec_b64 s[36:37], vcc
	s_cbranch_execz .LBB0_1723
	s_waitcnt lgkmcnt(0)
	v_add_f32_e32 v22, v22, v23
	ds_write_b32 v195, v22 offset:384
.LBB0_1723:
	s_or_b64 exec, exec, s[36:37]
	s_nop 0
	v_lshlrev_b32_e32 v22, 16, v36
	s_waitcnt lgkmcnt(0)
	v_and_b32_e32 v23, 0xffff0000, v36
	v_pk_fma_f32 v[22:23], v[12:13], v[136:137], v[22:23]
	v_lshlrev_b32_e32 v136, 16, v38
	v_and_b32_e32 v137, 0xffff0000, v38
	v_pk_fma_f32 v[128:129], v[8:9], v[128:129], v[136:137]
	v_lshlrev_b32_e32 v8, 16, v39
	v_and_b32_e32 v9, 0xffff0000, v39
	v_lshlrev_b32_e32 v12, 16, v37
	v_and_b32_e32 v13, 0xffff0000, v37
	v_pk_fma_f32 v[38:39], v[10:11], v[130:131], v[8:9]
	s_nop 0
	v_lshlrev_b32_e32 v130, 16, v32
	v_and_b32_e32 v131, 0xffff0000, v32
	v_pk_fma_f32 v[36:37], v[14:15], v[138:139], v[12:13]
	v_pk_mul_f32 v[8:9], v[128:129], v[128:129]
	v_pk_mul_f32 v[10:11], v[38:39], v[38:39]
	v_pk_fma_f32 v[130:131], v[4:5], v[140:141], v[130:131]
	v_lshlrev_b32_e32 v4, 16, v33
	v_and_b32_e32 v5, 0xffff0000, v33
	v_lshlrev_b32_e32 v136, 16, v34
	v_and_b32_e32 v137, 0xffff0000, v34
	v_pk_mul_f32 v[12:13], v[22:23], v[22:23]
	v_pk_mul_f32 v[14:15], v[36:37], v[36:37]
	v_pk_fma_f32 v[32:33], v[6:7], v[142:143], v[4:5]
	v_pk_fma_f32 v[132:133], v[0:1], v[132:133], v[136:137]
	v_lshlrev_b32_e32 v0, 16, v35
	v_and_b32_e32 v1, 0xffff0000, v35
	v_add_f32_e32 v10, v10, v11
	v_add_f32_e32 v8, v8, v9
	v_pk_mul_f32 v[4:5], v[130:131], v[130:131]
	v_pk_mul_f32 v[6:7], v[32:33], v[32:33]
	v_pk_fma_f32 v[34:35], v[2:3], v[134:135], v[0:1]
	v_add_f32_e32 v8, v8, v10
	v_add_f32_e32 v9, v14, v15
	v_add_f32_e32 v10, v12, v13
	v_pk_mul_f32 v[0:1], v[132:133], v[132:133]
	v_pk_mul_f32 v[2:3], v[34:35], v[34:35]
	v_add_f32_e32 v9, v10, v9
	v_add_f32_e32 v6, v6, v7
	v_add_f32_e32 v4, v4, v5
	v_add_f32_e32 v8, v9, v8
	v_add_f32_e32 v4, v4, v6
	v_add_f32_e32 v2, v2, v3
	v_add_f32_e32 v0, v0, v1
	v_add_f32_e32 v4, v8, v4
	v_add_f32_e32 v0, v0, v2
	v_add_f32_e32 v0, v0, v4
	ds_bpermute_b32 v1, v194, v0
	s_waitcnt lgkmcnt(0)
	v_add_f32_e32 v0, v0, v1
	ds_bpermute_b32 v1, v196, v0
	s_and_saveexec_b64 s[36:37], vcc
	s_cbranch_execz .LBB0_1725
	s_waitcnt lgkmcnt(0)
	v_add_f32_e32 v0, v0, v1
	ds_write_b32 v195, v0 offset:448
